# vG with the K-loop per-segment s_setprio 1/0 flips deleted (A/B of section 6.3 rule 2); nothing else changed
# baseline (speedup 1.0000x reference)
; #define PG8_STAGE(bufoff, gbase, voff) do { _Pragma("unroll") for (int _i = 0; _i < 2; ++_i) \
;         __builtin_amdgcn_global_load_lds((const unsigned*)((const char*)(gbase) + (voff)[_i]), (LAS unsigned*)(lds + (bufoff) + ldsw + _i * 8192), 16, 0, 0); } while (0)
; #define PG8_LDA(dst, b, h) do { _Pragma("unroll") for (int m = 0; m < 4; ++m) _Pragma("unroll") for (int k = 0; k < 2; ++k) dst[m][k] = *(const LAS bf16x8*)(lds + PG8_SA(b, h) + aoff + m * 2048 + k * 1024); } while (0)
; #define PG8_LDB(dst, b, h) do { _Pragma("unroll") for (int n = 0; n < 2; ++n) _Pragma("unroll") for (int k = 0; k < 2; ++k) dst[n][k] = *(const LAS bf16x8*)(lds + PG8_SB(b, h) + boff + n * 2048 + k * 1024); } while (0)
; #define PG8_MMA(ai, bj, At, Bt) do { __builtin_amdgcn_s_setprio(1); _Pragma("unroll") for (int m = 0; m < 4; ++m) _Pragma("unroll") for (int n = 0; n < 2; ++n) _Pragma("unroll") for (int k = 0; k < 2; ++k) \
;         acc[ai][bj][m][n] = __builtin_amdgcn_mfma_f32_16x16x32_bf16(Bt[n][k], At[m][k], acc[ai][bj][m][n], 0, 0, 0); __builtin_amdgcn_s_setprio(0); } while (0)
; #define PG8_WAIT_V(n) asm volatile("s_waitcnt vmcnt(" #n ")" ::: "memory")
; #define PG8_WAIT_L(n) asm volatile("s_waitcnt lgkmcnt(" #n ")" ::: "memory")
; #define PG8_BAR __builtin_amdgcn_s_barrier()
; #define PG8_SCHED __builtin_amdgcn_sched_barrier(0)
; __device__ __forceinline__ void gemm_phase(LAS unsigned char* lds, const Gemm g, const StaticOrder& S_, const Epi& E, const int tid) {
;     ...
;             PG8_LDB(B0, 0, 0); PG8_LDB(B1, 0, 1); PG8_SCHED; PG8_LDA(At, 0, 0); PG8_STAGE(PG8_SA(1, 1), a1 + hstep, voffA);
;             PG8_WAIT_V(8); PG8_WAIT_L(0); PG8_BAR; PG8_MMA(0, 0, At, B0); PG8_MMA(0, 1, At, B1); PG8_BAR; PG8_SCHED;
;             PG8_LDA(At, 0, 1); PG8_STAGE(PG8_SB(0, 0), b2, voffB); PG8_STAGE(PG8_SB(0, 1), b2 + hstep, voffB); PG8_STAGE(PG8_SA(0, 0), a2, voffA);
;             PG8_WAIT_V(8); PG8_WAIT_L(0); PG8_BAR; PG8_MMA(1, 0, At, B0); PG8_MMA(1, 1, At, B1); PG8_BAR; PG8_SCHED;
.LBB0_222:
	s_add_i32 s39, s20, 2
	s_add_u32 s96, s0, 0x80
	s_addc_u32 s21, s1, 0
	s_add_i32 s97, 0, 0x10000
	s_cmp_eq_u32 s9, s20
	s_cselect_b32 s21, s7, s21
	s_cselect_b32 s20, s6, s96
	v_add_u32_e32 v0, s97, v205
	s_cselect_b32 vcc_hi, s63, s38
	s_cselect_b32 vcc_lo, s62, s17
	s_add_i32 s96, 0, 0x14000
	ds_read_b128 v[130:133], v0
	ds_read_b128 v[134:137], v0 offset:1024
	ds_read_b128 v[138:141], v0 offset:2048
	ds_read_b128 v[142:145], v0 offset:3072
	v_add_u32_e32 v0, s96, v205
	ds_read_b128 v[146:149], v0
	ds_read_b128 v[150:153], v0 offset:1024
	ds_read_b128 v[154:157], v0 offset:2048
	ds_read_b128 v[158:161], v0 offset:3072
	v_lshl_add_u64 v[202:203], s[0:1], 0, v[194:195]
	s_add_i32 m0, s65, 0xc000
	ds_read_b128 v[162:165], v212
	ds_read_b128 v[166:169], v212 offset:1024
	ds_read_b128 v[170:173], v212 offset:2048
	ds_read_b128 v[174:177], v212 offset:3072
	ds_read_b128 v[178:181], v212 offset:4096
	ds_read_b128 v[182:185], v212 offset:5120
	ds_read_b128 v[198:201], v212 offset:6144
	ds_read_b128 v[214:217], v212 offset:7168
	global_load_lds_dwordx4 v[202:203], off
	v_lshl_add_u64 v[202:203], s[0:1], 0, v[196:197]
	s_add_i32 m0, s65, 0xe000
	s_nop 0
	global_load_lds_dwordx4 v[202:203], off
	s_waitcnt vmcnt(8)
	s_waitcnt lgkmcnt(0)
	s_barrier
	s_waitcnt lgkmcnt(0)
	v_mfma_f32_16x16x32_bf16 v[126:129], v[130:133], v[162:165], v[126:129]
	v_mfma_f32_16x16x32_bf16 v[122:125], v[138:141], v[162:165], v[122:125]
	v_mfma_f32_16x16x32_bf16 v[110:113], v[130:133], v[170:173], v[110:113]
	v_mfma_f32_16x16x32_bf16 v[106:109], v[138:141], v[170:173], v[106:109]
	v_mfma_f32_16x16x32_bf16 v[94:97], v[130:133], v[178:181], v[94:97]
	v_mfma_f32_16x16x32_bf16 v[90:93], v[138:141], v[178:181], v[90:93]
	v_mfma_f32_16x16x32_bf16 v[78:81], v[130:133], v[198:201], v[78:81]
	v_mfma_f32_16x16x32_bf16 v[74:77], v[138:141], v[198:201], v[74:77]
	v_mfma_f32_16x16x32_bf16 v[126:129], v[134:137], v[166:169], v[126:129]
	v_mfma_f32_16x16x32_bf16 v[122:125], v[142:145], v[166:169], v[122:125]
	v_mfma_f32_16x16x32_bf16 v[110:113], v[134:137], v[174:177], v[110:113]
	v_mfma_f32_16x16x32_bf16 v[106:109], v[142:145], v[174:177], v[106:109]
	v_mfma_f32_16x16x32_bf16 v[94:97], v[134:137], v[182:185], v[94:97]
	v_mfma_f32_16x16x32_bf16 v[90:93], v[142:145], v[182:185], v[90:93]
	v_mfma_f32_16x16x32_bf16 v[78:81], v[134:137], v[214:217], v[78:81]
	v_mfma_f32_16x16x32_bf16 v[74:77], v[142:145], v[214:217], v[74:77]
	v_mfma_f32_16x16x32_bf16 v[118:121], v[146:149], v[162:165], v[118:121]
	v_mfma_f32_16x16x32_bf16 v[114:117], v[154:157], v[162:165], v[114:117]
	v_mfma_f32_16x16x32_bf16 v[102:105], v[146:149], v[170:173], v[102:105]
	v_mfma_f32_16x16x32_bf16 v[98:101], v[154:157], v[170:173], v[98:101]
	v_mfma_f32_16x16x32_bf16 v[86:89], v[146:149], v[178:181], v[86:89]
	v_mfma_f32_16x16x32_bf16 v[82:85], v[154:157], v[178:181], v[82:85]
	v_mfma_f32_16x16x32_bf16 v[70:73], v[146:149], v[198:201], v[70:73]
	v_mfma_f32_16x16x32_bf16 v[66:69], v[154:157], v[198:201], v[66:69]
	v_mfma_f32_16x16x32_bf16 v[118:121], v[150:153], v[166:169], v[118:121]
	v_mfma_f32_16x16x32_bf16 v[114:117], v[158:161], v[166:169], v[114:117]
	v_mfma_f32_16x16x32_bf16 v[102:105], v[150:153], v[174:177], v[102:105]
	v_mfma_f32_16x16x32_bf16 v[98:101], v[158:161], v[174:177], v[98:101]
	v_mfma_f32_16x16x32_bf16 v[86:89], v[150:153], v[182:185], v[86:89]
	v_mfma_f32_16x16x32_bf16 v[82:85], v[158:161], v[182:185], v[82:85]
	v_mfma_f32_16x16x32_bf16 v[70:73], v[150:153], v[214:217], v[70:73]
	v_mfma_f32_16x16x32_bf16 v[66:69], v[158:161], v[214:217], v[66:69]
	s_barrier
	s_add_i32 s97, s97, s60
	v_lshl_add_u64 v[202:203], vcc, 0, v[188:189]
	s_mov_b32 m0, s97
	ds_read_b128 v[162:165], v212 offset:16384
	ds_read_b128 v[166:169], v212 offset:17408
	ds_read_b128 v[170:173], v212 offset:18432
	ds_read_b128 v[174:177], v212 offset:19456
	ds_read_b128 v[178:181], v212 offset:20480
	ds_read_b128 v[182:185], v212 offset:21504
	ds_read_b128 v[198:201], v212 offset:22528
	ds_read_b128 v[214:217], v212 offset:23552
	global_load_lds_dwordx4 v[202:203], off
	s_add_i32 m0, s97, 0x2000
	v_lshl_add_u64 v[218:219], vcc, 0, v[192:193]
	s_add_u32 vcc_lo, vcc_lo, s14
	s_addc_u32 vcc_hi, vcc_hi, 0
	s_add_i32 s96, s96, s60
	global_load_lds_dwordx4 v[218:219], off
	v_lshl_add_u64 v[220:221], vcc, 0, v[188:189]
	s_mov_b32 m0, s96
	v_lshl_add_u64 v[222:223], vcc, 0, v[192:193]
	global_load_lds_dwordx4 v[220:221], off
	s_add_i32 m0, s96, 0x2000
	v_lshl_add_u64 v[224:225], s[20:21], 0, v[186:187]
	global_load_lds_dwordx4 v[222:223], off
	s_mov_b32 m0, s65
	v_lshl_add_u64 v[226:227], s[20:21], 0, v[190:191]
	global_load_lds_dwordx4 v[224:225], off
	s_mov_b32 m0, s66
	s_nop 0
	global_load_lds_dwordx4 v[226:227], off
	s_waitcnt vmcnt(8)
	s_waitcnt lgkmcnt(0)
	s_barrier
; #define PG8_STAGE(bufoff, gbase, voff) do { _Pragma("unroll") for (int _i = 0; _i < 2; ++_i) \
;         __builtin_amdgcn_global_load_lds((const unsigned*)((const char*)(gbase) + (voff)[_i]), (LAS unsigned*)(lds + (bufoff) + ldsw + _i * 8192), 16, 0, 0); } while (0)
; #define PG8_LDA(dst, b, h) do { _Pragma("unroll") for (int m = 0; m < 4; ++m) _Pragma("unroll") for (int k = 0; k < 2; ++k) dst[m][k] = *(const LAS bf16x8*)(lds + PG8_SA(b, h) + aoff + m * 2048 + k * 1024); } while (0)
; #define PG8_LDB(dst, b, h) do { _Pragma("unroll") for (int n = 0; n < 2; ++n) _Pragma("unroll") for (int k = 0; k < 2; ++k) dst[n][k] = *(const LAS bf16x8*)(lds + PG8_SB(b, h) + boff + n * 2048 + k * 1024); } while (0)
; #define PG8_MMA(ai, bj, At, Bt) do { __builtin_amdgcn_s_setprio(1); _Pragma("unroll") for (int m = 0; m < 4; ++m) _Pragma("unroll") for (int n = 0; n < 2; ++n) _Pragma("unroll") for (int k = 0; k < 2; ++k) \
;         acc[ai][bj][m][n] = __builtin_amdgcn_mfma_f32_16x16x32_bf16(Bt[n][k], At[m][k], acc[ai][bj][m][n], 0, 0, 0); __builtin_amdgcn_s_setprio(0); } while (0)
; #define PG8_WAIT_V(n) asm volatile("s_waitcnt vmcnt(" #n ")" ::: "memory")
; #define PG8_WAIT_L(n) asm volatile("s_waitcnt lgkmcnt(" #n ")" ::: "memory")
; #define PG8_BAR __builtin_amdgcn_s_barrier()
; #define PG8_SCHED __builtin_amdgcn_sched_barrier(0)
; __device__ __forceinline__ void gemm_phase(LAS unsigned char* lds, const Gemm g, const StaticOrder& S_, const Epi& E, const int tid) {
;     ...
;             PG8_WAIT_V(8); PG8_WAIT_L(0); PG8_BAR; PG8_MMA(1, 0, At, B0); PG8_MMA(1, 1, At, B1); PG8_BAR; PG8_SCHED;
;             PG8_LDB(B0, 1, 0); PG8_LDB(B1, 1, 1); PG8_SCHED; PG8_LDA(At, 1, 0); PG8_STAGE(PG8_SA(0, 1), a2 + hstep, voffA);
;             PG8_WAIT_V(8); PG8_WAIT_L(0); PG8_BAR; PG8_MMA(0, 0, At, B0); PG8_MMA(0, 1, At, B1); PG8_BAR; PG8_SCHED;
	s_waitcnt lgkmcnt(0)
	v_mfma_f32_16x16x32_bf16 v[62:65], v[130:133], v[162:165], v[62:65]
	v_mfma_f32_16x16x32_bf16 v[58:61], v[138:141], v[162:165], v[58:61]
	v_mfma_f32_16x16x32_bf16 v[46:49], v[130:133], v[170:173], v[46:49]
	v_mfma_f32_16x16x32_bf16 v[42:45], v[138:141], v[170:173], v[42:45]
	v_mfma_f32_16x16x32_bf16 v[30:33], v[130:133], v[178:181], v[30:33]
	v_mfma_f32_16x16x32_bf16 v[26:29], v[138:141], v[178:181], v[26:29]
	v_mfma_f32_16x16x32_bf16 v[14:17], v[130:133], v[198:201], v[14:17]
	v_mfma_f32_16x16x32_bf16 v[10:13], v[138:141], v[198:201], v[10:13]
	v_mfma_f32_16x16x32_bf16 v[62:65], v[134:137], v[166:169], v[62:65]
	v_mfma_f32_16x16x32_bf16 v[58:61], v[142:145], v[166:169], v[58:61]
	v_mfma_f32_16x16x32_bf16 v[46:49], v[134:137], v[174:177], v[46:49]
	v_mfma_f32_16x16x32_bf16 v[42:45], v[142:145], v[174:177], v[42:45]
	v_mfma_f32_16x16x32_bf16 v[30:33], v[134:137], v[182:185], v[30:33]
	v_mfma_f32_16x16x32_bf16 v[26:29], v[142:145], v[182:185], v[26:29]
	v_mfma_f32_16x16x32_bf16 v[14:17], v[134:137], v[214:217], v[14:17]
	v_mfma_f32_16x16x32_bf16 v[10:13], v[142:145], v[214:217], v[10:13]
	v_mfma_f32_16x16x32_bf16 v[54:57], v[146:149], v[162:165], v[54:57]
	v_mfma_f32_16x16x32_bf16 v[50:53], v[154:157], v[162:165], v[50:53]
	v_mfma_f32_16x16x32_bf16 v[38:41], v[146:149], v[170:173], v[38:41]
	v_mfma_f32_16x16x32_bf16 v[34:37], v[154:157], v[170:173], v[34:37]
	v_mfma_f32_16x16x32_bf16 v[22:25], v[146:149], v[178:181], v[22:25]
	v_mfma_f32_16x16x32_bf16 v[18:21], v[154:157], v[178:181], v[18:21]
	v_mfma_f32_16x16x32_bf16 v[6:9], v[146:149], v[198:201], v[6:9]
	v_mfma_f32_16x16x32_bf16 v[2:5], v[154:157], v[198:201], v[2:5]
	v_mfma_f32_16x16x32_bf16 v[54:57], v[150:153], v[166:169], v[54:57]
	v_mfma_f32_16x16x32_bf16 v[50:53], v[158:161], v[166:169], v[50:53]
	v_mfma_f32_16x16x32_bf16 v[38:41], v[150:153], v[174:177], v[38:41]
	v_mfma_f32_16x16x32_bf16 v[34:37], v[158:161], v[174:177], v[34:37]
	v_mfma_f32_16x16x32_bf16 v[22:25], v[150:153], v[182:185], v[22:25]
	v_mfma_f32_16x16x32_bf16 v[18:21], v[158:161], v[182:185], v[18:21]
	v_mfma_f32_16x16x32_bf16 v[6:9], v[150:153], v[214:217], v[6:9]
	v_mfma_f32_16x16x32_bf16 v[2:5], v[158:161], v[214:217], v[2:5]
	s_barrier
	s_add_i32 s96, 0, 0x18000
	v_add_u32_e32 v0, s96, v205
	s_add_i32 s97, 0, 0x1c000
	ds_read_b128 v[130:133], v0
	ds_read_b128 v[134:137], v0 offset:1024
	ds_read_b128 v[138:141], v0 offset:2048
	ds_read_b128 v[142:145], v0 offset:3072
	v_add_u32_e32 v0, s97, v205
	ds_read_b128 v[146:149], v0
	ds_read_b128 v[150:153], v0 offset:1024
	ds_read_b128 v[154:157], v0 offset:2048
	ds_read_b128 v[158:161], v0 offset:3072
	s_add_u32 s20, s20, s14
	s_addc_u32 s21, s21, 0
	s_mov_b32 m0, s67
	v_lshl_add_u64 v[228:229], s[20:21], 0, v[186:187]
	ds_read_b128 v[162:165], v212 offset:32768
	ds_read_b128 v[166:169], v212 offset:33792
	ds_read_b128 v[170:173], v212 offset:34816
	ds_read_b128 v[174:177], v212 offset:35840
	ds_read_b128 v[178:181], v212 offset:36864
	ds_read_b128 v[182:185], v212 offset:37888
	ds_read_b128 v[198:201], v212 offset:38912
	ds_read_b128 v[214:217], v212 offset:39936
	global_load_lds_dwordx4 v[228:229], off
	v_lshl_add_u64 v[228:229], s[20:21], 0, v[190:191]
	s_mov_b32 m0, s56
	s_nop 0
	global_load_lds_dwordx4 v[228:229], off
	s_waitcnt vmcnt(8)
	s_waitcnt lgkmcnt(0)
	s_barrier
	s_waitcnt lgkmcnt(0)
	v_mfma_f32_16x16x32_bf16 v[126:129], v[130:133], v[162:165], v[126:129]
	v_mfma_f32_16x16x32_bf16 v[122:125], v[138:141], v[162:165], v[122:125]
	v_mfma_f32_16x16x32_bf16 v[110:113], v[130:133], v[170:173], v[110:113]
	v_mfma_f32_16x16x32_bf16 v[106:109], v[138:141], v[170:173], v[106:109]
	v_mfma_f32_16x16x32_bf16 v[94:97], v[130:133], v[178:181], v[94:97]
	v_mfma_f32_16x16x32_bf16 v[90:93], v[138:141], v[178:181], v[90:93]
	v_mfma_f32_16x16x32_bf16 v[78:81], v[130:133], v[198:201], v[78:81]
	v_mfma_f32_16x16x32_bf16 v[74:77], v[138:141], v[198:201], v[74:77]
	v_mfma_f32_16x16x32_bf16 v[126:129], v[134:137], v[166:169], v[126:129]
	v_mfma_f32_16x16x32_bf16 v[122:125], v[142:145], v[166:169], v[122:125]
	v_mfma_f32_16x16x32_bf16 v[110:113], v[134:137], v[174:177], v[110:113]
	v_mfma_f32_16x16x32_bf16 v[106:109], v[142:145], v[174:177], v[106:109]
	v_mfma_f32_16x16x32_bf16 v[94:97], v[134:137], v[182:185], v[94:97]
	v_mfma_f32_16x16x32_bf16 v[90:93], v[142:145], v[182:185], v[90:93]
	v_mfma_f32_16x16x32_bf16 v[78:81], v[134:137], v[214:217], v[78:81]
	v_mfma_f32_16x16x32_bf16 v[74:77], v[142:145], v[214:217], v[74:77]
	v_mfma_f32_16x16x32_bf16 v[118:121], v[146:149], v[162:165], v[118:121]
	v_mfma_f32_16x16x32_bf16 v[114:117], v[154:157], v[162:165], v[114:117]
	v_mfma_f32_16x16x32_bf16 v[102:105], v[146:149], v[170:173], v[102:105]
	v_mfma_f32_16x16x32_bf16 v[98:101], v[154:157], v[170:173], v[98:101]
	v_mfma_f32_16x16x32_bf16 v[86:89], v[146:149], v[178:181], v[86:89]
	v_mfma_f32_16x16x32_bf16 v[82:85], v[154:157], v[178:181], v[82:85]
	v_mfma_f32_16x16x32_bf16 v[70:73], v[146:149], v[198:201], v[70:73]
	v_mfma_f32_16x16x32_bf16 v[66:69], v[154:157], v[198:201], v[66:69]
	v_mfma_f32_16x16x32_bf16 v[118:121], v[150:153], v[166:169], v[118:121]
	v_mfma_f32_16x16x32_bf16 v[114:117], v[158:161], v[166:169], v[114:117]
	v_mfma_f32_16x16x32_bf16 v[102:105], v[150:153], v[174:177], v[102:105]
	v_mfma_f32_16x16x32_bf16 v[98:101], v[158:161], v[174:177], v[98:101]
	v_mfma_f32_16x16x32_bf16 v[86:89], v[150:153], v[182:185], v[86:89]
	v_mfma_f32_16x16x32_bf16 v[82:85], v[158:161], v[182:185], v[82:85]
	v_mfma_f32_16x16x32_bf16 v[70:73], v[150:153], v[214:217], v[70:73]
	v_mfma_f32_16x16x32_bf16 v[66:69], v[158:161], v[214:217], v[66:69]
	s_barrier
; #define PG8_STAGE(bufoff, gbase, voff) do { _Pragma("unroll") for (int _i = 0; _i < 2; ++_i) \
;         __builtin_amdgcn_global_load_lds((const unsigned*)((const char*)(gbase) + (voff)[_i]), (LAS unsigned*)(lds + (bufoff) + ldsw + _i * 8192), 16, 0, 0); } while (0)
; #define PG8_LDA(dst, b, h) do { _Pragma("unroll") for (int m = 0; m < 4; ++m) _Pragma("unroll") for (int k = 0; k < 2; ++k) dst[m][k] = *(const LAS bf16x8*)(lds + PG8_SA(b, h) + aoff + m * 2048 + k * 1024); } while (0)
; #define PG8_MMA(ai, bj, At, Bt) do { __builtin_amdgcn_s_setprio(1); _Pragma("unroll") for (int m = 0; m < 4; ++m) _Pragma("unroll") for (int n = 0; n < 2; ++n) _Pragma("unroll") for (int k = 0; k < 2; ++k) \
;         acc[ai][bj][m][n] = __builtin_amdgcn_mfma_f32_16x16x32_bf16(Bt[n][k], At[m][k], acc[ai][bj][m][n], 0, 0, 0); __builtin_amdgcn_s_setprio(0); } while (0)
; #define PG8_WAIT_V(n) asm volatile("s_waitcnt vmcnt(" #n ")" ::: "memory")
; #define PG8_WAIT_L(n) asm volatile("s_waitcnt lgkmcnt(" #n ")" ::: "memory")
; #define PG8_BAR __builtin_amdgcn_s_barrier()
; #define PG8_SCHED __builtin_amdgcn_sched_barrier(0)
; __device__ __forceinline__ void gemm_phase(LAS unsigned char* lds, const Gemm g, const StaticOrder& S_, const Epi& E, const int tid) {
;     ...
;         for (int t = 0; t < nt; t += 2) {
;     ...
;             PG8_LDA(At, 1, 1); PG8_STAGE(PG8_SB(1, 0), b3, voffB); PG8_STAGE(PG8_SB(1, 1), b3 + hstep, voffB); PG8_STAGE(PG8_SA(1, 0), a3, voffA);
;             PG8_WAIT_V(8); PG8_WAIT_L(0); PG8_BAR; PG8_MMA(1, 0, At, B0); PG8_MMA(1, 1, At, B1); PG8_BAR; PG8_SCHED;
	s_add_i32 s20, s96, s60
	v_lshl_add_u64 v[202:203], v[202:203], 0, s[34:35]
	s_mov_b32 m0, s20
	ds_read_b128 v[162:165], v212 offset:49152
	ds_read_b128 v[166:169], v212 offset:50176
	ds_read_b128 v[170:173], v212 offset:51200
	ds_read_b128 v[174:177], v212 offset:52224
	ds_read_b128 v[178:181], v212 offset:53248
	ds_read_b128 v[182:185], v212 offset:54272
	ds_read_b128 v[198:201], v212 offset:55296
	ds_read_b128 v[214:217], v212 offset:56320
	global_load_lds_dwordx4 v[202:203], off
	v_lshl_add_u64 v[202:203], v[218:219], 0, s[34:35]
	s_add_i32 m0, s20, 0x2000
	s_add_i32 s20, s97, s60
	global_load_lds_dwordx4 v[202:203], off
	v_lshl_add_u64 v[202:203], v[220:221], 0, s[34:35]
	s_mov_b32 m0, s20
	s_nop 0
	global_load_lds_dwordx4 v[202:203], off
	v_lshl_add_u64 v[202:203], v[222:223], 0, s[34:35]
	s_add_i32 m0, s20, 0x2000
	s_nop 0
	global_load_lds_dwordx4 v[202:203], off
	v_lshl_add_u64 v[202:203], v[224:225], 0, s[34:35]
	s_mov_b32 m0, s28
	s_nop 0
	global_load_lds_dwordx4 v[202:203], off
	v_lshl_add_u64 v[202:203], v[226:227], 0, s[34:35]
	s_mov_b32 m0, s40
	s_nop 0
	global_load_lds_dwordx4 v[202:203], off
	s_waitcnt vmcnt(8)
	s_waitcnt lgkmcnt(0)
	s_barrier
	s_waitcnt lgkmcnt(0)
	v_mfma_f32_16x16x32_bf16 v[62:65], v[130:133], v[162:165], v[62:65]
	v_mfma_f32_16x16x32_bf16 v[58:61], v[138:141], v[162:165], v[58:61]
	v_mfma_f32_16x16x32_bf16 v[46:49], v[130:133], v[170:173], v[46:49]
	v_mfma_f32_16x16x32_bf16 v[42:45], v[138:141], v[170:173], v[42:45]
	v_mfma_f32_16x16x32_bf16 v[30:33], v[130:133], v[178:181], v[30:33]
	v_mfma_f32_16x16x32_bf16 v[26:29], v[138:141], v[178:181], v[26:29]
	v_mfma_f32_16x16x32_bf16 v[14:17], v[130:133], v[198:201], v[14:17]
	v_mfma_f32_16x16x32_bf16 v[10:13], v[138:141], v[198:201], v[10:13]
	v_mfma_f32_16x16x32_bf16 v[62:65], v[134:137], v[166:169], v[62:65]
	v_mfma_f32_16x16x32_bf16 v[58:61], v[142:145], v[166:169], v[58:61]
	v_mfma_f32_16x16x32_bf16 v[46:49], v[134:137], v[174:177], v[46:49]
	v_mfma_f32_16x16x32_bf16 v[42:45], v[142:145], v[174:177], v[42:45]
	v_mfma_f32_16x16x32_bf16 v[30:33], v[134:137], v[182:185], v[30:33]
	v_mfma_f32_16x16x32_bf16 v[26:29], v[142:145], v[182:185], v[26:29]
	v_mfma_f32_16x16x32_bf16 v[14:17], v[134:137], v[214:217], v[14:17]
	v_mfma_f32_16x16x32_bf16 v[10:13], v[142:145], v[214:217], v[10:13]
	v_mfma_f32_16x16x32_bf16 v[54:57], v[146:149], v[162:165], v[54:57]
	v_mfma_f32_16x16x32_bf16 v[50:53], v[154:157], v[162:165], v[50:53]
	v_mfma_f32_16x16x32_bf16 v[38:41], v[146:149], v[170:173], v[38:41]
	v_mfma_f32_16x16x32_bf16 v[34:37], v[154:157], v[170:173], v[34:37]
	v_mfma_f32_16x16x32_bf16 v[22:25], v[146:149], v[178:181], v[22:25]
	v_mfma_f32_16x16x32_bf16 v[18:21], v[154:157], v[178:181], v[18:21]
	v_mfma_f32_16x16x32_bf16 v[6:9], v[146:149], v[198:201], v[6:9]
	v_mfma_f32_16x16x32_bf16 v[2:5], v[154:157], v[198:201], v[2:5]
	v_mfma_f32_16x16x32_bf16 v[54:57], v[150:153], v[166:169], v[54:57]
	v_mfma_f32_16x16x32_bf16 v[50:53], v[158:161], v[166:169], v[50:53]
	v_mfma_f32_16x16x32_bf16 v[38:41], v[150:153], v[174:177], v[38:41]
	v_mfma_f32_16x16x32_bf16 v[34:37], v[158:161], v[174:177], v[34:37]
	v_mfma_f32_16x16x32_bf16 v[22:25], v[150:153], v[182:185], v[22:25]
	v_mfma_f32_16x16x32_bf16 v[18:21], v[158:161], v[182:185], v[18:21]
	v_mfma_f32_16x16x32_bf16 v[6:9], v[150:153], v[214:217], v[6:9]
	v_mfma_f32_16x16x32_bf16 v[2:5], v[158:161], v[214:217], v[2:5]
	s_barrier
	s_add_u32 s0, s0, 0x100
	s_addc_u32 s1, s1, 0
	s_add_u32 s17, s17, 0x100
	s_addc_u32 s38, s38, 0
	s_cmp_ge_u32 s39, s8
	s_mov_b32 s20, s39
	s_cbranch_scc0 .LBB0_222
	s_and_b64 vcc, exec, s[10:11]
	s_cbranch_vccz .LBB0_225
	s_barrier
